# post-phase L1 row loop restructured the same way as L0 (Z-row loads hoisted into one prefetch burst per row)
# speedup vs baseline: 1.0009x; 1.0009x over previous
; __device__ __forceinline__ unsigned cvt_pk_bf16(float lo, float hi) { unsigned r; asm volatile("v_cvt_pk_bf16_f32 %0, %1, %2" : "=v"(r) : "v"(lo), "v"(hi)); return r; }
; __device__ __forceinline__ float lo_f(unsigned w) { return __uint_as_float(w << 16); }
; __device__ __forceinline__ float hi_f(unsigned w) { return __uint_as_float(w & 0xffff0000u); }
; __device__ void phase_post(const Ctx& c, int l, bool ctx_full) {
;     ...
;                 const u32x4 bg = *(const u32x4*)(zr + OFF_CB + cc);
;                 u32x4 w;
;                 w.x = cvt_pk_bf16(a[0] * lo_f(bg.x), a[1] * hi_f(bg.x)); w.y = cvt_pk_bf16(a[2] * lo_f(bg.y), a[3] * hi_f(bg.y));
;                 w.z = cvt_pk_bf16(a[4] * lo_f(bg.z), a[5] * hi_f(bg.z)); w.w = cvt_pk_bf16(a[6] * lo_f(bg.w), a[7] * hi_f(bg.w));
;                 *(u32x4*)(AM1 + (size_t)row * 1024 + cc) = w; }
.LBB0_1445:
	s_or_b64 exec, exec, s[2:3]
	v_lshl_add_u64 v[38:39], v[38:39], 0, v[56:57]
	v_mov_b64_e32 v[38:39], v[180:181]
	v_mov_b64_e32 v[40:41], v[182:183]
	v_lshlrev_b32_e32 v47, 16, v39
	v_and_b32_e32 v39, 0xffff0000, v39
	v_lshlrev_b32_e32 v46, 16, v38
	v_and_b32_e32 v38, 0xffff0000, v38
	v_lshlrev_b32_e32 v48, 16, v40
	v_and_b32_e32 v40, 0xffff0000, v40
	v_lshlrev_b32_e32 v49, 16, v41
	v_and_b32_e32 v41, 0xffff0000, v41
	v_mul_f32_e32 v36, v36, v47
	v_mul_f32_e32 v37, v37, v39
	v_mul_f32_e32 v44, v44, v46
	v_mul_f32_e32 v38, v45, v38
	v_mul_f32_e32 v39, v34, v48
	v_mul_f32_e32 v40, v35, v40
	v_mul_f32_e32 v42, v42, v49
	v_mul_f32_e32 v41, v43, v41
	v_cvt_pk_bf16_f32 v34, v44, v38
	v_cvt_pk_bf16_f32 v35, v36, v37
	v_cvt_pk_bf16_f32 v36, v39, v40
	v_cvt_pk_bf16_f32 v37, v42, v41
	global_store_dwordx4 v[32:33], v[34:37], off offset:1024

; __device__ void phase_post(const Ctx& c, int l, bool ctx_full) {
;     ...
;     for (int row = c.bid * 8 + c.wave; row < TT; row += c.G * 8) {
;         const bool lat = row < TL; int b, t, slen;
;         if (lat) { b = row >> 11; t = row & 2047; slen = SEQL; } else { b = (row - TL) >> 8; t = (row - TL) & 255; slen = CTXL; }
;         const bool full = lat || ctx_full;
;         const bf16_t* zr = Z + (size_t)row * IN_DIM;
;         float cs[8], sn[8];
;         if (lat) { const float* rp = rope + ((size_t)t * 64 + axis * 32 + fb) * 2;
; #pragma unroll
;             for (int i = 0; i < 4; ++i) { const f32x4 v = *(const f32x4*)(rp + i * 4); cs[2 * i] = v[0]; sn[2 * i] = v[1]; cs[2 * i + 1] = v[2]; sn[2 * i + 1] = v[3]; } }
;     ...
;             if (full) raw = *(const u32x4*)(zr + hd * 128 + 8 * l16);
;             else raw = kv_share8(kvp + (size_t)(row - TL) * 1024 + grp * 128 + 8 * l16);
;             float own[8] = {lo_f(raw.x), hi_f(raw.x), lo_f(raw.y), hi_f(raw.y), lo_f(raw.z), hi_f(raw.z), lo_f(raw.w), hi_f(raw.w)};
;             float ss = 0.f;
; #pragma unroll
;             for (int i = 0; i < 8; ++i) ss += own[i] * own[i];
; #pragma unroll
;             for (int o = 8; o; o >>= 1) ss += __int_as_float(__builtin_amdgcn_ds_bpermute((c.lane ^ o) << 2, __float_as_int(ss)));
;             const float rstd = rsqrtf(ss * (1.f / 128.f) + EPS);
;             u32x4 pr;
;             pr.x = (unsigned)__builtin_amdgcn_ds_bpermute((c.lane ^ 4) << 2, (int)raw.x); pr.y = (unsigned)__builtin_amdgcn_ds_bpermute((c.lane ^ 4) << 2, (int)raw.y);
;             pr.z = (unsigned)__builtin_amdgcn_ds_bpermute((c.lane ^ 4) << 2, (int)raw.z); pr.w = (unsigned)__builtin_amdgcn_ds_bpermute((c.lane ^ 4) << 2, (int)raw.w);
;             const float par[8] = {lo_f(pr.x), hi_f(pr.x), lo_f(pr.y), hi_f(pr.y), lo_f(pr.z), hi_f(pr.z), lo_f(pr.w), hi_f(pr.w)};
;             float o8[8];
; #pragma unroll
;             for (int i = 0; i < 8; ++i) { const float on = own[i] * rstd * (p < 4 ? gqo[i] : gko[i]), pn = par[i] * rstd * (p < 4 ? gqp[i] : gkp[i]);
;                 o8[i] = firsth ? on * cs[i] - pn * sn[i] : on * cs[i] + pn * sn[i]; }
;             u32x4 w; w.x = cvt_pk_bf16(o8[0], o8[1]); w.y = cvt_pk_bf16(o8[2], o8[3]); w.z = cvt_pk_bf16(o8[4], o8[5]); w.w = cvt_pk_bf16(o8[6], o8[7]);
;             if (p < 4) *(u32x4*)(Qo + (size_t)row * DM + hd * 128 + 8 * l16) = w;
.LBB0_1447:
	v_cmp_gt_i32_e64 s[6:7], s75, v52
	v_cmp_lt_i32_e32 vcc, s23, v52
	v_mov_b32_e32 v48, 4
	v_cndmask_b32_e64 v32, v125, v126, s[6:7]
	v_and_b32_e32 v127, v32, v52
	v_mov_b32_e32 v32, 1.0
	v_mov_b32_e32 v33, 0
	v_mov_b32_e32 v35, 0
	v_mov_b32_e32 v37, 0
	v_mov_b32_e32 v39, 0
	v_mov_b32_e32 v41, 0
	v_mov_b32_e32 v43, 0
	v_mov_b32_e32 v45, 0
	v_mov_b32_e32 v47, 0
	v_mov_b32_e32 v34, 1.0
	v_mov_b32_e32 v36, 1.0
	v_mov_b32_e32 v38, 1.0
	v_mov_b32_e32 v40, 1.0
	v_mov_b32_e32 v42, 1.0
	v_mov_b32_e32 v44, 1.0
	v_mov_b32_e32 v46, 1.0
	s_and_saveexec_b64 s[2:3], s[6:7]
	s_cbranch_execz .LBB0_1449
	v_mov_b32_e32 v242, v123
	v_mov_b32_e32 v243, 0
	v_lshl_add_u64 v[244:245], v[88:89], 0, v[242:243]
	v_mov_b32_e32 v242, 0x1000
	v_lshl_add_u64 v[234:235], v[244:245], 0, v[242:243]
	v_mov_b32_e32 v242, 0x3000
	v_lshl_add_u64 v[236:237], v[244:245], 0, v[242:243]
	v_mov_b32_e32 v242, 0x7000
	v_lshl_add_u64 v[240:241], v[236:237], 0, v[242:243]
	v_mov_b32_e32 v242, 0xffff9000
	v_mov_b32_e32 v243, -1
	v_lshl_add_u64 v[238:239], v[236:237], 0, v[242:243]
	global_load_dwordx4 v[148:151], v[234:235], off offset:-4096
	global_load_dwordx4 v[152:155], v[234:235], off offset:-3072
	global_load_dwordx4 v[156:159], v[234:235], off offset:-2048
	global_load_dwordx4 v[160:163], v[234:235], off offset:-1024
	global_load_dwordx4 v[164:167], v[234:235], off
	global_load_dwordx4 v[168:171], v[236:237], off offset:-4096
	global_load_dwordx4 v[172:175], v[236:237], off offset:-3072
	global_load_dwordx4 v[176:179], v[236:237], off offset:-2048
	global_load_dwordx4 v[180:183], v[236:237], off offset:-1024
	global_load_dwordx4 v[192:195], v[236:237], off
	global_load_dwordx4 v[196:199], v[236:237], off offset:2048
	global_load_dwordx4 v[218:221], v[236:237], off offset:1024
	global_load_dwordx4 v[222:225], v[236:237], off offset:3072
	global_load_dwordx4 v[184:187], v[238:239], off
	global_load_dwordx4 v[188:191], v[238:239], off offset:2048
	global_load_dwordx4 v[208:211], v[238:239], off offset:1024
	global_load_dwordx4 v[212:215], v[238:239], off offset:3072
	global_load_dwordx4 v[200:203], v[240:241], off
	global_load_dwordx4 v[204:207], v[240:241], off offset:2048
	global_load_dwordx4 v[226:229], v[240:241], off offset:1024
	global_load_dwordx4 v[230:233], v[240:241], off offset:3072
	v_lshl_or_b32 v44, v127, 9, v122
	global_load_dwordx4 v[32:35], v44, s[16:17]
	global_load_dwordx4 v[36:39], v44, s[16:17] offset:16
	global_load_dwordx4 v[40:43], v44, s[16:17] offset:32
	s_nop 0
	global_load_dwordx4 v[44:47], v44, s[16:17] offset:48
	v_mov_b32_e32 v48, 0
	s_waitcnt vmcnt(0)

; __device__ __forceinline__ unsigned cvt_pk_bf16(float lo, float hi) { unsigned r; asm volatile("v_cvt_pk_bf16_f32 %0, %1, %2" : "=v"(r) : "v"(lo), "v"(hi)); return r; }
; __device__ __forceinline__ float lo_f(unsigned w) { return __uint_as_float(w << 16); }
; __device__ __forceinline__ float hi_f(unsigned w) { return __uint_as_float(w & 0xffff0000u); }
; __device__ void phase_post(const Ctx& c, int l, bool ctx_full) {
;     ...
;         for (int p = full ? 0 : 4; p < 5; ++p) {
;             const int hd = 4 * p + grp;
;             u32x4 raw;
;             if (full) raw = *(const u32x4*)(zr + hd * 128 + 8 * l16);
;             else raw = kv_share8(kvp + (size_t)(row - TL) * 1024 + grp * 128 + 8 * l16);
;             float own[8] = {lo_f(raw.x), hi_f(raw.x), lo_f(raw.y), hi_f(raw.y), lo_f(raw.z), hi_f(raw.z), lo_f(raw.w), hi_f(raw.w)};
;             float ss = 0.f;
; #pragma unroll
;             for (int i = 0; i < 8; ++i) ss += own[i] * own[i];
; #pragma unroll
;             for (int o = 8; o; o >>= 1) ss += __int_as_float(__builtin_amdgcn_ds_bpermute((c.lane ^ o) << 2, __float_as_int(ss)));
;             const float rstd = rsqrtf(ss * (1.f / 128.f) + EPS);
;             u32x4 pr;
;             pr.x = (unsigned)__builtin_amdgcn_ds_bpermute((c.lane ^ 4) << 2, (int)raw.x); pr.y = (unsigned)__builtin_amdgcn_ds_bpermute((c.lane ^ 4) << 2, (int)raw.y);
;             pr.z = (unsigned)__builtin_amdgcn_ds_bpermute((c.lane ^ 4) << 2, (int)raw.z); pr.w = (unsigned)__builtin_amdgcn_ds_bpermute((c.lane ^ 4) << 2, (int)raw.w);
;             const float par[8] = {lo_f(pr.x), hi_f(pr.x), lo_f(pr.y), hi_f(pr.y), lo_f(pr.z), hi_f(pr.z), lo_f(pr.w), hi_f(pr.w)};
;             float o8[8];
; #pragma unroll
;             for (int i = 0; i < 8; ++i) { const float on = own[i] * rstd * (p < 4 ? gqo[i] : gko[i]), pn = par[i] * rstd * (p < 4 ? gqp[i] : gkp[i]);
;                 o8[i] = firsth ? on * cs[i] - pn * sn[i] : on * cs[i] + pn * sn[i]; }
;             u32x4 w; w.x = cvt_pk_bf16(o8[0], o8[1]); w.y = cvt_pk_bf16(o8[2], o8[3]); w.z = cvt_pk_bf16(o8[4], o8[5]); w.w = cvt_pk_bf16(o8[6], o8[7]);
;             if (p < 4) *(u32x4*)(Qo + (size_t)row * DM + hd * 128 + 8 * l16) = w;
.LBB0_1453:
	s_andn2_saveexec_b64 s[2:3], s[2:3]
	s_cbranch_execz .LBB0_1455
	v_mov_b64_e32 v[48:49], v[148:149]
	v_mov_b64_e32 v[50:51], v[150:151]
	v_mov_b64_e32 v[148:149], v[152:153]
	v_mov_b64_e32 v[150:151], v[154:155]
	v_mov_b64_e32 v[152:153], v[156:157]
	v_mov_b64_e32 v[154:155], v[158:159]
	v_mov_b64_e32 v[156:157], v[160:161]
	v_mov_b64_e32 v[158:159], v[162:163]
	v_mov_b64_e32 v[160:161], v[164:165]
	v_mov_b64_e32 v[162:163], v[166:167]
.LBB0_1455:
	s_or_b64 exec, exec, s[2:3]
	v_and_b32_e32 v136, 0xffff0000, v48
	v_lshlrev_b32_e32 v56, 16, v48
	v_mul_f32_e32 v132, v136, v136
	v_and_b32_e32 v128, 0xffff0000, v49
	v_lshlrev_b32_e32 v129, 16, v49
	v_fmac_f32_e32 v132, v56, v56
	v_pk_mul_f32 v[130:131], v[128:129], v[128:129]
	ds_bpermute_b32 v48, v67, v48
	v_add_f32_e32 v131, v131, v132
	v_add_f32_e32 v134, v130, v131
	v_and_b32_e32 v130, 0xffff0000, v50
	v_lshlrev_b32_e32 v131, 16, v50
	v_pk_mul_f32 v[132:133], v[130:131], v[130:131]
	v_cmp_eq_u32_e64 s[6:7], 3, v53
	v_add_f32_e32 v133, v133, v134
	v_add_f32_e32 v137, v132, v133
	v_and_b32_e32 v132, 0xffff0000, v51
	v_lshlrev_b32_e32 v133, 16, v51
	v_pk_mul_f32 v[134:135], v[132:133], v[132:133]
	v_cndmask_b32_e64 v140, v0, v4, s[6:7]
	v_add_f32_e32 v135, v135, v137
	v_add_f32_e32 v134, v134, v135
	ds_bpermute_b32 v135, v55, v134
	s_waitcnt lgkmcnt(1)
	v_lshlrev_b32_e32 v137, 16, v48
	ds_bpermute_b32 v49, v67, v49
	v_and_b32_e32 v48, 0xffff0000, v48
	ds_bpermute_b32 v50, v67, v50
	s_waitcnt lgkmcnt(2)
	v_add_f32_e32 v134, v134, v135
	ds_bpermute_b32 v135, v67, v134
	ds_bpermute_b32 v51, v67, v51
	s_waitcnt lgkmcnt(1)
	v_add_f32_e32 v134, v134, v135
	ds_bpermute_b32 v135, v118, v134
	s_waitcnt lgkmcnt(1)
	v_lshlrev_b32_e32 v139, 16, v51
	v_and_b32_e32 v51, 0xffff0000, v51
	s_waitcnt lgkmcnt(0)
	v_add_f32_e32 v134, v134, v135
	ds_bpermute_b32 v135, v119, v134
	s_waitcnt lgkmcnt(0)
	v_add_f32_e32 v134, v134, v135
	v_fmamk_f32 v134, v134, 0x3c000000, v124
	v_mul_f32_e32 v135, 0x4b800000, v134
	v_cmp_gt_f32_e64 s[2:3], s78, v134
	s_nop 1
	v_cndmask_b32_e64 v134, v134, v135, s[2:3]
	v_rsq_f32_e32 v134, v134
	v_lshlrev_b32_e32 v135, 16, v49
	v_and_b32_e32 v49, 0xffff0000, v49
	v_mul_f32_e32 v138, 0x45800000, v134
	v_cndmask_b32_e64 v134, v134, v138, s[2:3]
	v_mul_f32_e32 v56, v134, v56
	v_mul_f32_e32 v56, v140, v56
	v_mul_f32_e32 v137, v134, v137
	v_cndmask_b32_e64 v140, v16, v20, s[6:7]
	v_mul_f32_e32 v137, v140, v137
	v_mul_f32_e32 v137, v33, v137
	v_cndmask_b32_e64 v137, v137, -v137, s[4:5]
	v_fmac_f32_e32 v137, v32, v56
	v_mul_f32_e32 v56, v134, v136
	v_cndmask_b32_e64 v136, v1, v5, s[6:7]
	v_mul_f32_e32 v56, v136, v56
	v_mul_f32_e32 v48, v134, v48
	v_cndmask_b32_e64 v136, v17, v21, s[6:7]
	v_mul_f32_e32 v48, v136, v48
	v_mul_f32_e32 v48, v35, v48
	v_cndmask_b32_e64 v48, v48, -v48, s[4:5]
	v_fmac_f32_e32 v48, v34, v56
	v_mul_f32_e32 v56, v134, v129
	v_cndmask_b32_e64 v129, v2, v6, s[6:7]
	v_mul_f32_e32 v56, v129, v56
	v_mul_f32_e32 v129, v134, v135
	v_cndmask_b32_e64 v135, v18, v22, s[6:7]
	v_mul_f32_e32 v129, v135, v129
	v_mul_f32_e32 v129, v37, v129
	v_cndmask_b32_e64 v129, v129, -v129, s[4:5]
	v_fmac_f32_e32 v129, v36, v56
	v_mul_f32_e32 v56, v134, v128
	v_cndmask_b32_e64 v128, v3, v7, s[6:7]
	v_mul_f32_e32 v56, v128, v56
	v_mul_f32_e32 v49, v134, v49
	v_cndmask_b32_e64 v128, v19, v23, s[6:7]
	v_mul_f32_e32 v49, v128, v49
	v_mul_f32_e32 v49, v39, v49
	v_cndmask_b32_e64 v49, v49, -v49, s[4:5]
	v_lshlrev_b32_e32 v138, 16, v50
	v_fmac_f32_e32 v49, v38, v56
	v_mul_f32_e32 v56, v134, v131
	v_cndmask_b32_e64 v128, v8, v12, s[6:7]
	v_mul_f32_e32 v56, v128, v56
	v_mul_f32_e32 v128, v134, v138
	v_cndmask_b32_e64 v131, v24, v28, s[6:7]
	v_mul_f32_e32 v128, v131, v128
	v_mul_f32_e32 v128, v41, v128
	v_cndmask_b32_e64 v128, v128, -v128, s[4:5]
	v_and_b32_e32 v50, 0xffff0000, v50
	v_fmac_f32_e32 v128, v40, v56
	v_mul_f32_e32 v56, v134, v130
	v_cndmask_b32_e64 v130, v9, v13, s[6:7]
	v_mul_f32_e32 v56, v130, v56
	v_mul_f32_e32 v50, v134, v50
	v_cndmask_b32_e64 v130, v25, v29, s[6:7]
	v_mul_f32_e32 v50, v130, v50
	v_mul_f32_e32 v50, v43, v50
	v_cndmask_b32_e64 v50, v50, -v50, s[4:5]
	v_fmac_f32_e32 v50, v42, v56
	v_mul_f32_e32 v56, v134, v133
	v_cndmask_b32_e64 v130, v10, v14, s[6:7]
	v_mul_f32_e32 v56, v130, v56
	v_mul_f32_e32 v130, v134, v139
	v_cndmask_b32_e64 v131, v26, v30, s[6:7]
	v_mul_f32_e32 v130, v131, v130
	v_mul_f32_e32 v130, v45, v130
	v_cndmask_b32_e64 v130, v130, -v130, s[4:5]
	v_fmac_f32_e32 v130, v44, v56
	v_mul_f32_e32 v56, v134, v132
	v_cndmask_b32_e64 v131, v11, v15, s[6:7]
	v_mul_f32_e32 v56, v131, v56
	v_mul_f32_e32 v51, v134, v51
	v_cndmask_b32_e64 v131, v27, v31, s[6:7]
	v_mul_f32_e32 v51, v131, v51
	v_mul_f32_e32 v51, v47, v51
	v_cndmask_b32_e64 v51, v51, -v51, s[4:5]
	v_cmp_ne_u32_e64 s[2:3], 3, v53
	v_fmac_f32_e32 v51, v46, v56
	v_cvt_pk_bf16_f32 v48, v137, v48
	v_cvt_pk_bf16_f32 v49, v129, v49
	v_cvt_pk_bf16_f32 v50, v128, v50
	v_cvt_pk_bf16_f32 v51, v130, v51
	s_and_saveexec_b64 s[6:7], s[2:3]
	s_xor_b64 s[2:3], exec, s[6:7]
	s_cbranch_execz .LBB0_1457
	global_store_dwordx4 v[116:117], v[48:51], off

; __device__ __forceinline__ float lo_f(unsigned w) { return __uint_as_float(w << 16); }
; __device__ __forceinline__ float hi_f(unsigned w) { return __uint_as_float(w & 0xffff0000u); }
; __device__ __forceinline__ float gelu_tanh(float x) {
;     const float y = 0.7978845608028654f * (x + 0.044715f * x * x * x);
;     const float e = __expf(2.f * y);
;     const float th = 1.f - 2.f / (e + 1.f);
;     return 0.5f * x * (1.f + th);
; }
; __device__ void phase_post(const Ctx& c, int l, bool ctx_full) {
;     ...
;         if (full) {
;             float fv[16]; float ss = 0.f;
; #pragma unroll
;             for (int i = 0; i < 2; ++i) { const int cc = i * 512 + c.lane * 8;
;                 const u32x4 zv = *(const u32x4*)(zr + OFF_GV + cc);
;                 fv[i * 8 + 0] = gelu_tanh(lo_f(zv.x)); fv[i * 8 + 1] = gelu_tanh(hi_f(zv.x)); fv[i * 8 + 2] = gelu_tanh(lo_f(zv.y)); fv[i * 8 + 3] = gelu_tanh(hi_f(zv.y));
;                 fv[i * 8 + 4] = gelu_tanh(lo_f(zv.z)); fv[i * 8 + 5] = gelu_tanh(hi_f(zv.z)); fv[i * 8 + 6] = gelu_tanh(lo_f(zv.w)); fv[i * 8 + 7] = gelu_tanh(hi_f(zv.w));
; #pragma unroll
;                 for (int j = 0; j < 8; ++j) ss += fv[i * 8 + j] * fv[i * 8 + j]; }
.LBB0_1461:
	s_or_saveexec_b64 s[72:73], s[2:3]
	v_ashrrev_i32_e32 v53, 31, v52
	s_xor_b64 exec, exec, s[72:73]
	s_cbranch_execz .LBB0_1446
	v_mov_b64_e32 v[32:33], s[14:15]
	v_mad_i64_i32 v[40:41], s[2:3], v52, s74, v[32:33]
	v_lshlrev_b32_e32 v56, 1, v54
	v_lshl_add_u64 v[42:43], v[40:41], 0, v[56:57]
	v_add_co_u32_e32 v32, vcc, 0x2000, v42
	s_nop 1
	v_addc_co_u32_e32 v33, vcc, 0, v43, vcc
	v_mov_b64_e32 v[36:37], v[168:169]
	v_mov_b64_e32 v[38:39], v[170:171]
	v_lshl_add_u64 v[32:33], v[42:43], 0, s[20:21]
	v_mov_b64_e32 v[32:33], v[172:173]
	v_mov_b64_e32 v[34:35], v[174:175]
	v_lshlrev_b32_e32 v44, 16, v36
	v_and_b32_e32 v36, 0xffff0000, v36
	v_mul_f32_e32 v47, 0x3d372713, v44
	v_lshlrev_b32_e32 v45, 16, v37
	v_mul_f32_e32 v49, 0x3d372713, v36
	v_mul_f32_e32 v47, v47, v44
	v_mul_f32_e32 v48, 0.5, v44
	v_mul_f32_e32 v51, 0x3d372713, v45
	v_mul_f32_e32 v49, v49, v36
	v_fma_f32 v44, v47, v44, v44
	v_mul_f32_e32 v50, 0.5, v36
	v_mul_f32_e32 v51, v51, v45
	v_fma_f32 v36, v49, v36, v36
	v_mul_f32_e32 v44, 0x3f4c422a, v44
	v_mul_f32_e32 v92, 0.5, v45
	v_fma_f32 v45, v51, v45, v45
	v_mul_f32_e32 v36, 0x3f4c422a, v36
	v_add_f32_e32 v44, v44, v44
	v_mul_f32_e32 v45, 0x3f4c422a, v45
	v_add_f32_e32 v36, v36, v36
	v_mul_f32_e32 v44, 0x3fb8aa3b, v44
	v_add_f32_e32 v45, v45, v45
	v_mul_f32_e32 v36, 0x3fb8aa3b, v36
	v_exp_f32_e32 v44, v44
	v_mul_f32_e32 v45, 0x3fb8aa3b, v45
	v_exp_f32_e32 v36, v36
	v_exp_f32_e32 v45, v45
	v_and_b32_e32 v37, 0xffff0000, v37
	v_mul_f32_e32 v93, 0x3d372713, v37
	v_add_f32_e32 v44, 1.0, v44
	v_mul_f32_e32 v93, v93, v37
	v_add_f32_e32 v36, 1.0, v36
	v_div_scale_f32 v49, s[2:3], v44, v44, 2.0
	v_fma_f32 v47, v93, v37, v37
	v_add_f32_e32 v45, 1.0, v45
	v_div_scale_f32 v93, s[2:3], v36, v36, 2.0
	v_rcp_f32_e32 v99, v49
	v_div_scale_f32 v95, s[6:7], v45, v45, 2.0
	v_rcp_f32_e32 v100, v93
	v_rcp_f32_e32 v101, v95
	v_fma_f32 v103, -v49, v99, 1.0
	v_div_scale_f32 v51, vcc, 2.0, v44, 2.0
	v_fma_f32 v104, -v93, v100, 1.0
	v_fmac_f32_e32 v99, v103, v99
	v_div_scale_f32 v94, s[2:3], 2.0, v36, 2.0
	v_fma_f32 v105, -v95, v101, 1.0
	v_fmac_f32_e32 v100, v104, v100
	v_mul_f32_e32 v103, v51, v99
	v_div_scale_f32 v96, s[6:7], 2.0, v45, 2.0
	v_fmac_f32_e32 v101, v105, v101
	v_mul_f32_e32 v104, v94, v100
	v_fma_f32 v107, -v49, v103, v51
	v_mul_f32_e32 v47, 0x3f4c422a, v47
	v_mul_f32_e32 v105, v96, v101
	v_fma_f32 v108, -v93, v104, v94
	v_fmac_f32_e32 v103, v107, v99
	v_add_f32_e32 v47, v47, v47
	v_fma_f32 v109, -v95, v105, v96
	v_fmac_f32_e32 v104, v108, v100
	v_fma_f32 v49, -v49, v103, v51
	v_mul_f32_e32 v47, 0x3fb8aa3b, v47
	v_fmac_f32_e32 v105, v109, v101
	v_fma_f32 v51, -v93, v104, v94
	v_div_fmas_f32 v49, v49, v99, v103
	s_mov_b64 vcc, s[2:3]
	v_exp_f32_e32 v47, v47
	v_fma_f32 v93, -v95, v105, v96
	v_div_fixup_f32 v44, v49, v44, 2.0
	v_div_fmas_f32 v49, v51, v100, v104
	s_mov_b64 vcc, s[6:7]
	v_sub_f32_e32 v44, 1.0, v44
	v_div_fixup_f32 v36, v49, v36, 2.0
	v_div_fmas_f32 v49, v93, v101, v105
	v_add_f32_e32 v44, 1.0, v44
	v_sub_f32_e32 v36, 1.0, v36
	v_div_fixup_f32 v45, v49, v45, 2.0
	v_mul_f32_e32 v51, v48, v44
	v_add_f32_e32 v36, 1.0, v36
	v_sub_f32_e32 v44, 1.0, v45
	v_lshlrev_b32_e32 v46, 16, v38
	v_add_f32_e32 v47, 1.0, v47
	v_mul_f32_e32 v50, v50, v36
	v_add_f32_e32 v36, 1.0, v44
	v_div_scale_f32 v97, s[8:9], v47, v47, 2.0
	v_mul_f32_e32 v92, v92, v36
	v_mul_f32_e32 v36, 0x3d372713, v46
	v_rcp_f32_e32 v102, v97
	v_mul_f32_e32 v36, v36, v46
	v_fma_f32 v36, v36, v46, v46
	v_mul_f32_e32 v36, 0x3f4c422a, v36
	v_add_f32_e32 v36, v36, v36
	v_fma_f32 v106, -v97, v102, 1.0
	v_mul_f32_e32 v36, 0x3fb8aa3b, v36
	v_div_scale_f32 v98, s[8:9], 2.0, v47, 2.0
	v_fmac_f32_e32 v102, v106, v102
	v_exp_f32_e32 v36, v36
	v_mul_f32_e32 v106, v98, v102
	v_fma_f32 v110, -v97, v106, v98
	v_fmac_f32_e32 v106, v110, v102
	v_fma_f32 v94, -v97, v106, v98
	s_mov_b64 vcc, s[8:9]
	v_add_f32_e32 v36, 1.0, v36
	v_div_fmas_f32 v44, v94, v102, v106
	v_div_scale_f32 v45, s[2:3], v36, v36, 2.0
	v_div_fixup_f32 v44, v44, v47, 2.0
	v_rcp_f32_e32 v47, v45
	v_sub_f32_e32 v44, 1.0, v44
	v_mul_f32_e32 v37, 0.5, v37
	v_add_f32_e32 v44, 1.0, v44
	v_mul_f32_e32 v93, v37, v44
	v_fma_f32 v37, -v45, v47, 1.0
	v_fmac_f32_e32 v47, v37, v47
	v_div_scale_f32 v37, vcc, 2.0, v36, 2.0
	v_mul_f32_e32 v44, v37, v47
	v_fma_f32 v48, -v45, v44, v37
	v_fmac_f32_e32 v44, v48, v47
	v_and_b32_e32 v38, 0xffff0000, v38
	v_fma_f32 v37, -v45, v44, v37
	v_mul_f32_e32 v45, 0x3d372713, v38
	v_mul_f32_e32 v45, v45, v38
	v_fma_f32 v45, v45, v38, v38
	v_mul_f32_e32 v45, 0x3f4c422a, v45
	v_add_f32_e32 v45, v45, v45
	v_mul_f32_e32 v45, 0x3fb8aa3b, v45
	v_exp_f32_e32 v45, v45
	v_div_fmas_f32 v37, v37, v47, v44
	v_div_fixup_f32 v36, v37, v36, 2.0
	v_sub_f32_e32 v36, 1.0, v36
	v_add_f32_e32 v37, 1.0, v45
	v_div_scale_f32 v44, s[2:3], v37, v37, 2.0
	v_rcp_f32_e32 v45, v44
	v_mul_f32_e32 v46, 0.5, v46
	v_add_f32_e32 v36, 1.0, v36
	v_mul_f32_e32 v94, v46, v36
	v_fma_f32 v36, -v44, v45, 1.0
	v_fmac_f32_e32 v45, v36, v45
	v_div_scale_f32 v36, vcc, 2.0, v37, 2.0
	v_mul_f32_e32 v46, v36, v45
	v_fma_f32 v47, -v44, v46, v36
	v_fmac_f32_e32 v46, v47, v45
	v_fma_f32 v36, -v44, v46, v36
	v_lshlrev_b32_e32 v44, 16, v39
	v_mul_f32_e32 v47, 0x3d372713, v44
	v_mul_f32_e32 v47, v47, v44
	v_fma_f32 v47, v47, v44, v44
	v_mul_f32_e32 v47, 0x3f4c422a, v47
	v_add_f32_e32 v47, v47, v47
	v_mul_f32_e32 v47, 0x3fb8aa3b, v47
	v_exp_f32_e32 v47, v47
	v_div_fmas_f32 v36, v36, v45, v46
	v_div_fixup_f32 v36, v36, v37, 2.0
	v_sub_f32_e32 v36, 1.0, v36
	v_add_f32_e32 v37, 1.0, v47
	v_div_scale_f32 v45, s[2:3], v37, v37, 2.0
	v_rcp_f32_e32 v46, v45
	v_mul_f32_e32 v38, 0.5, v38
	v_add_f32_e32 v36, 1.0, v36
	v_mul_f32_e32 v95, v38, v36
; __device__ __forceinline__ float lo_f(unsigned w) { return __uint_as_float(w << 16); }
; __device__ __forceinline__ float hi_f(unsigned w) { return __uint_as_float(w & 0xffff0000u); }
; __device__ __forceinline__ float gelu_tanh(float x) {
;     const float y = 0.7978845608028654f * (x + 0.044715f * x * x * x);
;     const float e = __expf(2.f * y);
;     const float th = 1.f - 2.f / (e + 1.f);
;     return 0.5f * x * (1.f + th);
; }
; __device__ void phase_post(const Ctx& c, int l, bool ctx_full) {
;     ...
;             for (int i = 0; i < 2; ++i) { const int cc = i * 512 + c.lane * 8;
;                 const u32x4 zv = *(const u32x4*)(zr + OFF_GV + cc);
;                 fv[i * 8 + 0] = gelu_tanh(lo_f(zv.x)); fv[i * 8 + 1] = gelu_tanh(hi_f(zv.x)); fv[i * 8 + 2] = gelu_tanh(lo_f(zv.y)); fv[i * 8 + 3] = gelu_tanh(hi_f(zv.y));
;                 fv[i * 8 + 4] = gelu_tanh(lo_f(zv.z)); fv[i * 8 + 5] = gelu_tanh(hi_f(zv.z)); fv[i * 8 + 6] = gelu_tanh(lo_f(zv.w)); fv[i * 8 + 7] = gelu_tanh(hi_f(zv.w));
; #pragma unroll
;                 for (int j = 0; j < 8; ++j) ss += fv[i * 8 + j] * fv[i * 8 + j]; }
;             ss = wave_sum(ss, c.lane); const float rstd = rsqrtf(ss * (1.f / 1024.f) + EPS);
	v_fma_f32 v36, -v45, v46, 1.0
	v_fmac_f32_e32 v46, v36, v46
	v_div_scale_f32 v36, vcc, 2.0, v37, 2.0
	v_mul_f32_e32 v38, v36, v46
	v_fma_f32 v47, -v45, v38, v36
	v_fmac_f32_e32 v38, v47, v46
	v_and_b32_e32 v39, 0xffff0000, v39
	v_fma_f32 v36, -v45, v38, v36
	v_mul_f32_e32 v45, 0x3d372713, v39
	v_mul_f32_e32 v45, v45, v39
	v_fma_f32 v45, v45, v39, v39
	v_mul_f32_e32 v45, 0x3f4c422a, v45
	v_add_f32_e32 v45, v45, v45
	v_mul_f32_e32 v45, 0x3fb8aa3b, v45
	v_exp_f32_e32 v45, v45
	v_div_fmas_f32 v36, v36, v46, v38
	v_div_fixup_f32 v36, v36, v37, 2.0
	v_sub_f32_e32 v36, 1.0, v36
	v_add_f32_e32 v37, 1.0, v45
	v_div_scale_f32 v38, s[2:3], v37, v37, 2.0
	v_rcp_f32_e32 v45, v38
	v_mul_f32_e32 v44, 0.5, v44
	v_add_f32_e32 v36, 1.0, v36
	v_mul_f32_e32 v96, v44, v36
	v_fma_f32 v36, -v38, v45, 1.0
	v_fmac_f32_e32 v45, v36, v45
	v_div_scale_f32 v36, vcc, 2.0, v37, 2.0
	v_mul_f32_e32 v44, v36, v45
	v_fma_f32 v46, -v38, v44, v36
	v_fmac_f32_e32 v44, v46, v45
	v_fma_f32 v36, -v38, v44, v36
	v_div_fmas_f32 v36, v36, v45, v44
	v_div_fixup_f32 v36, v36, v37, 2.0
	v_sub_f32_e32 v36, 1.0, v36
	v_mul_f32_e32 v37, 0.5, v39
	v_add_f32_e32 v36, 1.0, v36
	v_mul_f32_e32 v97, v37, v36
	v_lshlrev_b32_e32 v36, 16, v32
	v_mul_f32_e32 v37, 0x3d372713, v36
	v_mul_f32_e32 v37, v37, v36
	v_fma_f32 v37, v37, v36, v36
	v_mul_f32_e32 v37, 0x3f4c422a, v37
	v_add_f32_e32 v37, v37, v37
	v_mul_f32_e32 v37, 0x3fb8aa3b, v37
	v_exp_f32_e32 v37, v37
	v_and_b32_e32 v32, 0xffff0000, v32
	v_mul_f32_e32 v36, 0.5, v36
	v_mul_f32_e32 v44, v50, v50
	v_add_f32_e32 v37, 1.0, v37
	v_div_scale_f32 v38, s[2:3], v37, v37, 2.0
	v_rcp_f32_e32 v39, v38
	v_fmac_f32_e32 v44, v51, v51
	v_fmac_f32_e32 v44, v92, v92
	v_fmac_f32_e32 v44, v93, v93
	v_fma_f32 v45, -v38, v39, 1.0
	v_fmac_f32_e32 v39, v45, v39
	v_div_scale_f32 v45, vcc, 2.0, v37, 2.0
	v_mul_f32_e32 v46, v45, v39
	v_fma_f32 v47, -v38, v46, v45
	v_fmac_f32_e32 v46, v47, v39
	v_fma_f32 v38, -v38, v46, v45
	v_mul_f32_e32 v45, 0x3d372713, v32
	v_mul_f32_e32 v45, v45, v32
	v_fma_f32 v45, v45, v32, v32
	v_mul_f32_e32 v45, 0x3f4c422a, v45
	v_add_f32_e32 v45, v45, v45
	v_mul_f32_e32 v45, 0x3fb8aa3b, v45
	v_exp_f32_e32 v45, v45
	v_div_fmas_f32 v38, v38, v39, v46
	v_div_fixup_f32 v37, v38, v37, 2.0
	v_sub_f32_e32 v37, 1.0, v37
	v_add_f32_e32 v38, 1.0, v45
	v_div_scale_f32 v39, s[2:3], v38, v38, 2.0
	v_rcp_f32_e32 v45, v39
	v_add_f32_e32 v37, 1.0, v37
	v_mul_f32_e32 v98, v36, v37
	v_mul_f32_e32 v32, 0.5, v32
	v_fma_f32 v36, -v39, v45, 1.0
	v_fmac_f32_e32 v45, v36, v45
	v_div_scale_f32 v36, vcc, 2.0, v38, 2.0
	v_mul_f32_e32 v37, v36, v45
	v_fma_f32 v46, -v39, v37, v36
	v_fmac_f32_e32 v37, v46, v45
	v_fma_f32 v36, -v39, v37, v36
	v_lshlrev_b32_e32 v39, 16, v33
	v_mul_f32_e32 v46, 0x3d372713, v39
	v_mul_f32_e32 v46, v46, v39
	v_fma_f32 v46, v46, v39, v39
	v_mul_f32_e32 v46, 0x3f4c422a, v46
	v_add_f32_e32 v46, v46, v46
	v_mul_f32_e32 v46, 0x3fb8aa3b, v46
	v_exp_f32_e32 v46, v46
	v_div_fmas_f32 v36, v36, v45, v37
	v_div_fixup_f32 v36, v36, v38, 2.0
	v_sub_f32_e32 v36, 1.0, v36
	v_add_f32_e32 v37, 1.0, v46
	v_div_scale_f32 v38, s[2:3], v37, v37, 2.0
	v_rcp_f32_e32 v45, v38
	v_add_f32_e32 v36, 1.0, v36
	v_mul_f32_e32 v99, v32, v36
	v_and_b32_e32 v33, 0xffff0000, v33
	v_fma_f32 v32, -v38, v45, 1.0
	v_fmac_f32_e32 v45, v32, v45
	v_div_scale_f32 v32, vcc, 2.0, v37, 2.0
	v_mul_f32_e32 v36, v32, v45
	v_fma_f32 v46, -v38, v36, v32
	v_fmac_f32_e32 v36, v46, v45
	v_fma_f32 v32, -v38, v36, v32
	v_mul_f32_e32 v38, 0x3d372713, v33
	v_mul_f32_e32 v38, v38, v33
	v_fma_f32 v38, v38, v33, v33
	v_mul_f32_e32 v38, 0x3f4c422a, v38
	v_add_f32_e32 v38, v38, v38
	v_mul_f32_e32 v38, 0x3fb8aa3b, v38
	v_exp_f32_e32 v38, v38
	v_div_fmas_f32 v32, v32, v45, v36
	v_div_fixup_f32 v32, v32, v37, 2.0
	v_sub_f32_e32 v32, 1.0, v32
	v_add_f32_e32 v36, 1.0, v38
	v_div_scale_f32 v37, s[2:3], v36, v36, 2.0
	v_rcp_f32_e32 v38, v37
	v_mul_f32_e32 v39, 0.5, v39
	v_add_f32_e32 v32, 1.0, v32
	v_mul_f32_e32 v100, v39, v32
	v_fma_f32 v32, -v37, v38, 1.0
	v_fmac_f32_e32 v38, v32, v38
	v_div_scale_f32 v32, vcc, 2.0, v36, 2.0
	v_mul_f32_e32 v39, v32, v38
	v_fma_f32 v45, -v37, v39, v32
	v_fmac_f32_e32 v39, v45, v38
	v_fma_f32 v32, -v37, v39, v32
	v_div_fmas_f32 v32, v32, v38, v39
	v_div_fixup_f32 v32, v32, v36, 2.0
	v_mul_f32_e32 v39, 0.5, v33
	v_lshlrev_b32_e32 v33, 16, v34
	v_sub_f32_e32 v38, 1.0, v32
	v_and_b32_e32 v32, 0xffff0000, v34
	v_mul_f32_e32 v34, 0x3d372713, v33
	v_mul_f32_e32 v34, v34, v33
	v_mov_b32_e32 v36, v33
	v_fmac_f32_e32 v36, v34, v36
	v_mul_f32_e32 v34, 0x3f4c422a, v36
	v_add_f32_e32 v34, v34, v34
	v_mul_f32_e32 v34, 0x3fb8aa3b, v34
	v_exp_f32_e32 v37, v34
	v_mul_f32_e32 v34, 0x3d372713, v32
	v_mul_f32_e32 v34, v34, v32
	v_mov_b32_e32 v36, v32
	v_fmac_f32_e32 v36, v34, v36
	v_mul_f32_e32 v34, 0x3f4c422a, v36
	v_add_f32_e32 v34, v34, v34
	v_mul_f32_e32 v34, 0x3fb8aa3b, v34
	v_exp_f32_e32 v36, v34
	v_add_f32_e32 v34, 1.0, v38
	v_mul_f32_e32 v101, v39, v34
	v_fmac_f32_e32 v44, v94, v94
	v_pk_add_f32 v[36:37], v[36:37], 1.0 op_sel_hi:[1,0]
	v_fmac_f32_e32 v44, v95, v95
	v_div_scale_f32 v34, s[2:3], v37, v37, 2.0
	v_rcp_f32_e32 v38, v34
	v_fmac_f32_e32 v44, v96, v96
	v_fmac_f32_e32 v44, v97, v97
	v_fmac_f32_e32 v44, v98, v98
	v_fma_f32 v39, -v34, v38, 1.0
	v_fmac_f32_e32 v38, v39, v38
	v_div_scale_f32 v39, vcc, 2.0, v37, 2.0
	v_mul_f32_e32 v45, v39, v38
	v_fma_f32 v46, -v34, v45, v39
	v_fmac_f32_e32 v45, v46, v38
	v_fma_f32 v34, -v34, v45, v39
	v_div_scale_f32 v39, s[2:3], v36, v36, 2.0
	v_rcp_f32_e32 v46, v39
	v_div_fmas_f32 v34, v34, v38, v45
	v_div_fixup_f32 v37, v34, v37, 2.0
	v_fmac_f32_e32 v44, v99, v99
	v_fma_f32 v34, -v39, v46, 1.0
	v_fmac_f32_e32 v46, v34, v46
	v_div_scale_f32 v34, vcc, 2.0, v36, 2.0
; __device__ __forceinline__ unsigned cvt_pk_bf16(float lo, float hi) { unsigned r; asm volatile("v_cvt_pk_bf16_f32 %0, %1, %2" : "=v"(r) : "v"(lo), "v"(hi)); return r; }
; __device__ __forceinline__ float lo_f(unsigned w) { return __uint_as_float(w << 16); }
; __device__ __forceinline__ float hi_f(unsigned w) { return __uint_as_float(w & 0xffff0000u); }
; __device__ void phase_post(const Ctx& c, int l, bool ctx_full) {
;     ...
;             ss = wave_sum(ss, c.lane); const float rstd = rsqrtf(ss * (1.f / 1024.f) + EPS);
; #pragma unroll
;             for (int i = 0; i < 2; ++i) { const int cc = i * 512 + c.lane * 8;
;                 const f32x4 g0 = *(const f32x4*)(gv + cc), g1 = *(const f32x4*)(gv + cc + 4);
;                 u32x4 w;
;                 w.x = cvt_pk_bf16(fv[i * 8 + 0] * rstd * g0[0], fv[i * 8 + 1] * rstd * g0[1]); w.y = cvt_pk_bf16(fv[i * 8 + 2] * rstd * g0[2], fv[i * 8 + 3] * rstd * g0[3]);
;                 w.z = cvt_pk_bf16(fv[i * 8 + 4] * rstd * g1[0], fv[i * 8 + 5] * rstd * g1[1]); w.w = cvt_pk_bf16(fv[i * 8 + 6] * rstd * g1[2], fv[i * 8 + 7] * rstd * g1[3]);
;                 *(u32x4*)(VN + (size_t)row * 1024 + cc) = w; }
; #pragma unroll
;             for (int i = 0; i < 2; ++i) { const int cc = i * 512 + c.lane * 8;
;                 float a[8] = {0.f, 0.f, 0.f, 0.f, 0.f, 0.f, 0.f, 0.f};
; #pragma unroll
;                 for (int k = 0; k < 3; ++k) { const int tt = t + k - 1;
;                     if (tt >= 0 && tt < slen) { const bf16_t* z2 = zr + (ptrdiff_t)(k - 1) * IN_DIM;
;                         const u32x4 cg = *(const u32x4*)(z2 + OFF_CC + cc), hh = *(const u32x4*)(z2 + OFF_CH + cc);
;                         const f32x4 w0 = *(const f32x4*)(wsc + k * 1024 + cc), w1 = *(const f32x4*)(wsc + k * 1024 + cc + 4);
;                         a[0] += w0[0] * lo_f(cg.x) * lo_f(hh.x); a[1] += w0[1] * hi_f(cg.x) * hi_f(hh.x); a[2] += w0[2] * lo_f(cg.y) * lo_f(hh.y); a[3] += w0[3] * hi_f(cg.y) * hi_f(hh.y);
;                         a[4] += w1[0] * lo_f(cg.z) * lo_f(hh.z); a[5] += w1[1] * hi_f(cg.z) * hi_f(hh.z); a[6] += w1[2] * lo_f(cg.w) * lo_f(hh.w); a[7] += w1[3] * hi_f(cg.w) * hi_f(hh.w); } }
	v_mul_f32_e32 v38, v34, v46
	v_fma_f32 v45, -v39, v38, v34
	v_fmac_f32_e32 v38, v45, v46
	v_fma_f32 v34, -v39, v38, v34
	v_div_fmas_f32 v34, v34, v46, v38
	v_lshlrev_b32_e32 v39, 16, v35
	v_div_fixup_f32 v36, v34, v36, 2.0
	v_mul_f32_e32 v34, 0x3d372713, v39
	v_and_b32_e32 v38, 0xffff0000, v35
	v_mul_f32_e32 v34, v34, v39
	v_mov_b32_e32 v35, v39
	v_fmac_f32_e32 v35, v34, v35
	v_mul_f32_e32 v34, 0x3f4c422a, v35
	v_add_f32_e32 v34, v34, v34
	v_mul_f32_e32 v34, 0x3fb8aa3b, v34
	v_exp_f32_e32 v35, v34
	v_mul_f32_e32 v34, 0x3d372713, v38
	v_mul_f32_e32 v34, v34, v38
	v_mov_b32_e32 v45, v38
	v_fmac_f32_e32 v45, v34, v45
	v_mul_f32_e32 v34, 0x3f4c422a, v45
	v_add_f32_e32 v34, v34, v34
	v_mul_f32_e32 v34, 0x3fb8aa3b, v34
	v_exp_f32_e32 v34, v34
	v_pk_add_f32 v[36:37], v[36:37], 1.0 op_sel_hi:[1,0] neg_lo:[1,0] neg_hi:[1,0]
	v_pk_mul_f32 v[32:33], v[32:33], 0.5 op_sel_hi:[1,0]
	v_pk_add_f32 v[36:37], v[36:37], 1.0 op_sel_hi:[1,0]
	v_fmac_f32_e32 v44, v100, v100
	v_pk_mul_f32 v[48:49], v[32:33], v[36:37]
	v_fmac_f32_e32 v44, v101, v101
	v_pk_add_f32 v[32:33], v[34:35], 1.0 op_sel_hi:[1,0]
	v_pk_mul_f32 v[34:35], v[48:49], v[48:49]
	v_div_scale_f32 v102, s[2:3], v33, v33, 2.0
	v_add_f32_e32 v35, v35, v44
	v_add_f32_e32 v104, v34, v35
	global_load_dwordx4 v[34:37], v[64:65], off offset:16
	global_load_dwordx4 v[44:47], v[64:65], off
	v_rcp_f32_e32 v103, v102
	v_pk_mul_f32 v[38:39], v[38:39], 0.5 op_sel_hi:[1,0]
	v_cmp_ne_u32_e64 s[6:7], 0, v127
	v_fma_f32 v105, -v102, v103, 1.0
	v_fmac_f32_e32 v103, v105, v103
	v_div_scale_f32 v105, vcc, 2.0, v33, 2.0
	v_mul_f32_e32 v106, v105, v103
	v_fma_f32 v107, -v102, v106, v105
	v_fmac_f32_e32 v106, v107, v103
	v_fma_f32 v102, -v102, v106, v105
	v_div_scale_f32 v105, s[2:3], v32, v32, 2.0
	v_rcp_f32_e32 v107, v105
	v_div_fmas_f32 v102, v102, v103, v106
	v_div_fixup_f32 v33, v102, v33, 2.0
	v_fma_f32 v102, -v105, v107, 1.0
	v_fmac_f32_e32 v107, v102, v107
	v_div_scale_f32 v102, vcc, 2.0, v32, 2.0
	v_mul_f32_e32 v103, v102, v107
	v_fma_f32 v106, -v105, v103, v102
	v_fmac_f32_e32 v103, v106, v107
	v_fma_f32 v102, -v105, v103, v102
	v_div_fmas_f32 v102, v102, v107, v103
	v_div_fixup_f32 v32, v102, v32, 2.0
	v_pk_add_f32 v[32:33], v[32:33], 1.0 op_sel_hi:[1,0] neg_lo:[1,0] neg_hi:[1,0]
	s_nop 0
	v_pk_add_f32 v[32:33], v[32:33], 1.0 op_sel_hi:[1,0]
	s_nop 0
	v_pk_mul_f32 v[38:39], v[38:39], v[32:33]
	s_nop 0
	v_pk_mul_f32 v[32:33], v[38:39], v[38:39]
	s_nop 0
	v_add_f32_e32 v33, v33, v104
	v_add_f32_e32 v32, v32, v33
	ds_bpermute_b32 v33, v120, v32
	s_waitcnt lgkmcnt(0)
	v_add_f32_e32 v32, v32, v33
	ds_bpermute_b32 v33, v121, v32
	s_waitcnt lgkmcnt(0)
	v_add_f32_e32 v32, v32, v33
	ds_bpermute_b32 v33, v55, v32
	s_waitcnt lgkmcnt(0)
	v_add_f32_e32 v32, v32, v33
	ds_bpermute_b32 v33, v67, v32
	s_waitcnt lgkmcnt(0)
	v_add_f32_e32 v32, v32, v33
	ds_bpermute_b32 v33, v118, v32
	s_waitcnt lgkmcnt(0)
	v_add_f32_e32 v32, v32, v33
	ds_bpermute_b32 v33, v119, v32
	s_waitcnt lgkmcnt(0)
	v_add_f32_e32 v32, v32, v33
	v_fmamk_f32 v32, v32, 0x3a800000, v124
	v_mul_f32_e32 v33, 0x4b800000, v32
	v_cmp_gt_f32_e32 vcc, s78, v32
	s_nop 1
	v_cndmask_b32_e32 v32, v32, v33, vcc
	v_rsq_f32_e32 v32, v32
	s_nop 0
	v_mul_f32_e32 v33, 0x45800000, v32
	v_cndmask_b32_e32 v102, v32, v33, vcc
	v_mul_f32_e32 v51, v51, v102
	v_mul_f32_e32 v50, v50, v102
	s_waitcnt vmcnt(0)
	v_mul_f32_e32 v44, v44, v51
	v_mul_f32_e32 v45, v45, v50
	v_cvt_pk_bf16_f32 v44, v44, v45
	v_mul_f32_e32 v45, v92, v102
	v_mul_f32_e32 v45, v46, v45
	v_mul_f32_e32 v46, v93, v102
	v_mul_f32_e32 v46, v47, v46
	v_cvt_pk_bf16_f32 v45, v45, v46
	v_mul_f32_e32 v46, v94, v102
	v_mul_f32_e32 v34, v34, v46
	v_mul_f32_e32 v46, v95, v102
	v_lshlrev_b64 v[32:33], 11, v[52:53]
	v_mul_f32_e32 v35, v35, v46
	v_cvt_pk_bf16_f32 v46, v34, v35
	v_mul_f32_e32 v34, v96, v102
	v_mul_f32_e32 v35, v97, v102
	v_lshl_add_u64 v[50:51], v[84:85], 0, v[32:33]
	v_mul_f32_e32 v34, v36, v34
	v_mul_f32_e32 v35, v37, v35
	v_cvt_pk_bf16_f32 v47, v34, v35
	global_store_dwordx4 v[50:51], v[44:47], off
	global_load_dwordx4 v[34:37], v[68:69], off
	s_nop 0
	global_load_dwordx4 v[44:47], v[68:69], off offset:16
	v_mul_f32_e32 v53, v98, v102
	v_mul_f32_e32 v38, v38, v102
	s_waitcnt vmcnt(1)
	v_mul_f32_e32 v34, v34, v53
	v_mul_f32_e32 v53, v99, v102
	v_mul_f32_e32 v35, v35, v53
	v_cvt_pk_bf16_f32 v34, v34, v35
	v_mul_f32_e32 v35, v100, v102
	v_mul_f32_e32 v35, v36, v35
	v_mul_f32_e32 v36, v101, v102
	v_mul_f32_e32 v36, v37, v36
	v_cvt_pk_bf16_f32 v35, v35, v36
	v_mul_f32_e32 v36, v49, v102
	v_mul_f32_e32 v37, v48, v102
	s_waitcnt vmcnt(0)
	v_mul_f32_e32 v36, v44, v36
	v_mul_f32_e32 v37, v45, v37
	v_cvt_pk_bf16_f32 v36, v36, v37
	v_mul_f32_e32 v37, v39, v102
	v_mul_f32_e32 v37, v46, v37
	v_mul_f32_e32 v38, v47, v38
	v_cvt_pk_bf16_f32 v37, v37, v38
	v_mov_b32_e32 v38, 0
	global_store_dwordx4 v[50:51], v[34:37], off offset:1024
	v_mov_b32_e32 v39, v38
	v_mov_b32_e32 v44, v38
	v_mov_b32_e32 v45, v38
	v_mov_b32_e32 v46, v38
	v_mov_b32_e32 v47, v38
	v_mov_b32_e32 v50, v38
	v_mov_b32_e32 v51, v38
	s_and_saveexec_b64 s[2:3], s[6:7]
	s_cbranch_execz .LBB0_1464
	v_add_co_u32_e32 v34, vcc, 0xffffc000, v42
	s_nop 1
	v_addc_co_u32_e32 v35, vcc, -1, v43, vcc
	v_mov_b64_e32 v[34:35], v[184:185]
	v_mov_b64_e32 v[36:37], v[186:187]
	v_add_co_u32_e32 v38, vcc, 0xffffd000, v42
	v_lshlrev_b32_e32 v50, 16, v36
	v_addc_co_u32_e32 v39, vcc, -1, v43, vcc
	global_load_dwordx4 v[42:45], v[70:71], off
	v_mov_b64_e32 v[46:47], v[188:189]
	v_mov_b64_e32 v[48:49], v[190:191]
	global_load_dwordx4 v[92:95], v[70:71], off offset:16
	v_lshlrev_b32_e32 v38, 16, v34
	v_and_b32_e32 v39, 0xffff0000, v34
	v_lshlrev_b32_e32 v34, 16, v35
	v_and_b32_e32 v35, 0xffff0000, v35
	v_and_b32_e32 v51, 0xffff0000, v36
	v_lshlrev_b32_e32 v36, 16, v37
	v_and_b32_e32 v37, 0xffff0000, v37
	s_waitcnt vmcnt(1)
	v_pk_mul_f32 v[38:39], v[42:43], v[38:39]
	s_waitcnt vmcnt(1)
	v_lshlrev_b32_e32 v42, 16, v46
	v_and_b32_e32 v43, 0xffff0000, v46
	v_pk_mul_f32 v[34:35], v[44:45], v[34:35]
	v_lshlrev_b32_e32 v44, 16, v47
	v_and_b32_e32 v45, 0xffff0000, v47
	s_waitcnt vmcnt(0)
	v_pk_mul_f32 v[46:47], v[92:93], v[50:51]
	v_lshlrev_b32_e32 v50, 16, v48
	v_and_b32_e32 v51, 0xffff0000, v48
	v_pk_mul_f32 v[36:37], v[94:95], v[36:37]
	v_lshlrev_b32_e32 v48, 16, v49
	v_and_b32_e32 v49, 0xffff0000, v49
	v_pk_fma_f32 v[38:39], v[38:39], v[42:43], 0 op_sel_hi:[1,1,0]
	v_pk_fma_f32 v[44:45], v[34:35], v[44:45], 0 op_sel_hi:[1,1,0]
	v_pk_fma_f32 v[46:47], v[46:47], v[50:51], 0 op_sel_hi:[1,1,0]
	v_pk_fma_f32 v[50:51], v[36:37], v[48:49], 0 op_sel_hi:[1,1,0]
; __device__ __forceinline__ float lo_f(unsigned w) { return __uint_as_float(w << 16); }
; __device__ __forceinline__ float hi_f(unsigned w) { return __uint_as_float(w & 0xffff0000u); }
; __device__ void phase_post(const Ctx& c, int l, bool ctx_full) {
;     ...
;                 for (int k = 0; k < 3; ++k) { const int tt = t + k - 1;
;                     if (tt >= 0 && tt < slen) { const bf16_t* z2 = zr + (ptrdiff_t)(k - 1) * IN_DIM;
;                         const u32x4 cg = *(const u32x4*)(z2 + OFF_CC + cc), hh = *(const u32x4*)(z2 + OFF_CH + cc);
;                         const f32x4 w0 = *(const f32x4*)(wsc + k * 1024 + cc), w1 = *(const f32x4*)(wsc + k * 1024 + cc + 4);
;                         a[0] += w0[0] * lo_f(cg.x) * lo_f(hh.x); a[1] += w0[1] * hi_f(cg.x) * hi_f(hh.x); a[2] += w0[2] * lo_f(cg.y) * lo_f(hh.y); a[3] += w0[3] * hi_f(cg.y) * hi_f(hh.y);
;                         a[4] += w1[0] * lo_f(cg.z) * lo_f(hh.z); a[5] += w1[1] * hi_f(cg.z) * hi_f(hh.z); a[6] += w1[2] * lo_f(cg.w) * lo_f(hh.w); a[7] += w1[3] * hi_f(cg.w) * hi_f(hh.w); } }
.LBB0_1464:
	s_or_b64 exec, exec, s[2:3]
	v_lshl_add_u64 v[34:35], v[40:41], 0, s[18:19]
	v_lshl_add_u64 v[36:37], v[34:35], 0, v[56:57]
	v_mov_b64_e32 v[92:93], v[192:193]
	v_mov_b64_e32 v[94:95], v[194:195]
	v_lshl_add_u64 v[36:37], v[40:41], 0, s[68:69]
	v_lshl_add_u64 v[42:43], v[36:37], 0, v[56:57]
	v_mov_b64_e32 v[96:97], v[196:197]
	v_mov_b64_e32 v[98:99], v[198:199]
	global_load_dwordx4 v[100:103], v[72:73], off
	global_load_dwordx4 v[104:107], v[72:73], off offset:16
	v_cmp_ne_u32_e64 s[8:9], s76, v127
	s_waitcnt vmcnt(3)
	v_lshlrev_b32_e32 v42, 16, v92
	v_and_b32_e32 v43, 0xffff0000, v92
	v_lshlrev_b32_e32 v92, 16, v93
	v_and_b32_e32 v93, 0xffff0000, v93
	v_lshlrev_b32_e32 v108, 16, v94
	v_and_b32_e32 v109, 0xffff0000, v94
	v_lshlrev_b32_e32 v94, 16, v95
	v_and_b32_e32 v95, 0xffff0000, v95
	s_waitcnt vmcnt(2)
	v_lshlrev_b32_e32 v48, 16, v96
	v_and_b32_e32 v49, 0xffff0000, v96
	v_lshlrev_b32_e32 v96, 16, v97
	v_and_b32_e32 v97, 0xffff0000, v97
	v_lshlrev_b32_e32 v110, 16, v98
	v_and_b32_e32 v111, 0xffff0000, v98
	v_lshlrev_b32_e32 v98, 16, v99
	v_and_b32_e32 v99, 0xffff0000, v99
	s_waitcnt vmcnt(1)
	v_pk_mul_f32 v[42:43], v[100:101], v[42:43]
	v_pk_mul_f32 v[92:93], v[102:103], v[92:93]
	s_waitcnt vmcnt(0)
	v_pk_mul_f32 v[100:101], v[104:105], v[108:109]
	v_pk_mul_f32 v[94:95], v[106:107], v[94:95]
	v_pk_fma_f32 v[48:49], v[42:43], v[48:49], v[38:39]
	v_pk_fma_f32 v[44:45], v[92:93], v[96:97], v[44:45]
	v_pk_fma_f32 v[42:43], v[100:101], v[110:111], v[46:47]
	v_pk_fma_f32 v[46:47], v[94:95], v[98:99], v[50:51]
	s_and_saveexec_b64 s[2:3], s[8:9]
	s_cbranch_execz .LBB0_1466
	v_lshl_add_u64 v[38:39], v[40:41], 0, v[56:57]
	v_add_co_u32_e32 v38, vcc, 0xa000, v38
	s_nop 1
	v_addc_co_u32_e32 v39, vcc, 0, v39, vcc
	v_mov_b64_e32 v[92:93], v[200:201]
	v_mov_b64_e32 v[94:95], v[202:203]
	v_mov_b64_e32 v[96:97], v[204:205]
	v_mov_b64_e32 v[98:99], v[206:207]
	global_load_dwordx4 v[100:103], v[74:75], off
	global_load_dwordx4 v[104:107], v[74:75], off offset:16
	s_waitcnt vmcnt(3)
	v_lshlrev_b32_e32 v38, 16, v92
	v_and_b32_e32 v39, 0xffff0000, v92
	v_lshlrev_b32_e32 v92, 16, v93
	v_and_b32_e32 v93, 0xffff0000, v93
	v_lshlrev_b32_e32 v108, 16, v94
	v_and_b32_e32 v109, 0xffff0000, v94
	v_lshlrev_b32_e32 v94, 16, v95
	v_and_b32_e32 v95, 0xffff0000, v95
	s_waitcnt vmcnt(2)
	v_lshlrev_b32_e32 v50, 16, v96
	v_and_b32_e32 v51, 0xffff0000, v96
	v_lshlrev_b32_e32 v96, 16, v97
	v_and_b32_e32 v97, 0xffff0000, v97
	v_lshlrev_b32_e32 v110, 16, v98
	v_and_b32_e32 v111, 0xffff0000, v98
	v_lshlrev_b32_e32 v98, 16, v99
	v_and_b32_e32 v99, 0xffff0000, v99
	s_waitcnt vmcnt(1)
	v_pk_mul_f32 v[38:39], v[100:101], v[38:39]
	v_pk_mul_f32 v[92:93], v[102:103], v[92:93]
	s_waitcnt vmcnt(0)
	v_pk_mul_f32 v[100:101], v[104:105], v[108:109]
	v_pk_mul_f32 v[94:95], v[106:107], v[94:95]
	v_pk_fma_f32 v[48:49], v[38:39], v[50:51], v[48:49]
	v_pk_fma_f32 v[44:45], v[92:93], v[96:97], v[44:45]
	v_pk_fma_f32 v[42:43], v[100:101], v[110:111], v[42:43]
	v_pk_fma_f32 v[46:47], v[94:95], v[98:99], v[46:47]
; __device__ __forceinline__ unsigned cvt_pk_bf16(float lo, float hi) { unsigned r; asm volatile("v_cvt_pk_bf16_f32 %0, %1, %2" : "=v"(r) : "v"(lo), "v"(hi)); return r; }
; __device__ __forceinline__ float lo_f(unsigned w) { return __uint_as_float(w << 16); }
; __device__ __forceinline__ float hi_f(unsigned w) { return __uint_as_float(w & 0xffff0000u); }
; __device__ void phase_post(const Ctx& c, int l, bool ctx_full) {
;     ...
;             for (int i = 0; i < 2; ++i) { const int cc = i * 512 + c.lane * 8;
;                 float a[8] = {0.f, 0.f, 0.f, 0.f, 0.f, 0.f, 0.f, 0.f};
; #pragma unroll
;                 for (int k = 0; k < 3; ++k) { const int tt = t + k - 1;
;                     if (tt >= 0 && tt < slen) { const bf16_t* z2 = zr + (ptrdiff_t)(k - 1) * IN_DIM;
;                         const u32x4 cg = *(const u32x4*)(z2 + OFF_CC + cc), hh = *(const u32x4*)(z2 + OFF_CH + cc);
;                         const f32x4 w0 = *(const f32x4*)(wsc + k * 1024 + cc), w1 = *(const f32x4*)(wsc + k * 1024 + cc + 4);
;                         a[0] += w0[0] * lo_f(cg.x) * lo_f(hh.x); a[1] += w0[1] * hi_f(cg.x) * hi_f(hh.x); a[2] += w0[2] * lo_f(cg.y) * lo_f(hh.y); a[3] += w0[3] * hi_f(cg.y) * hi_f(hh.y);
;                         a[4] += w1[0] * lo_f(cg.z) * lo_f(hh.z); a[5] += w1[1] * hi_f(cg.z) * hi_f(hh.z); a[6] += w1[2] * lo_f(cg.w) * lo_f(hh.w); a[7] += w1[3] * hi_f(cg.w) * hi_f(hh.w); } }
;                 const u32x4 bg = *(const u32x4*)(zr + OFF_CB + cc);
;                 u32x4 w;
;                 w.x = cvt_pk_bf16(a[0] * lo_f(bg.x), a[1] * hi_f(bg.x)); w.y = cvt_pk_bf16(a[2] * lo_f(bg.y), a[3] * hi_f(bg.y));
;                 w.z = cvt_pk_bf16(a[4] * lo_f(bg.z), a[5] * hi_f(bg.z)); w.w = cvt_pk_bf16(a[6] * lo_f(bg.w), a[7] * hi_f(bg.w));
;                 *(u32x4*)(AM1 + (size_t)row * 1024 + cc) = w; }
.LBB0_1466:
	s_or_b64 exec, exec, s[2:3]
	v_lshl_add_u64 v[38:39], v[40:41], 0, s[70:71]
	v_lshl_add_u64 v[50:51], v[38:39], 0, v[56:57]
	v_mov_b64_e32 v[98:99], v[176:177]
	v_mov_b64_e32 v[100:101], v[178:179]
	v_lshl_add_u64 v[32:33], v[86:87], 0, v[32:33]
	v_mov_b32_e32 v50, 0
	v_mov_b32_e32 v51, 0
	v_mov_b32_e32 v92, 0
	v_mov_b32_e32 v93, 0
	v_mov_b32_e32 v94, 0
	v_mov_b32_e32 v95, 0
	v_mov_b32_e32 v96, 0
	v_lshlrev_b32_e32 v56, 1, v66
	s_waitcnt vmcnt(0)
	v_lshlrev_b32_e32 v53, 16, v98
	v_and_b32_e32 v97, 0xffff0000, v98
	v_lshlrev_b32_e32 v98, 16, v99
	v_lshlrev_b32_e32 v102, 16, v100
	v_and_b32_e32 v100, 0xffff0000, v100
	v_and_b32_e32 v99, 0xffff0000, v99
	v_mul_f32_e32 v49, v49, v97
	v_mul_f32_e32 v44, v44, v98
	v_mul_f32_e32 v97, v43, v100
	v_lshlrev_b32_e32 v103, 16, v101
	v_and_b32_e32 v101, 0xffff0000, v101
	v_mul_f32_e32 v48, v48, v53
	v_mul_f32_e32 v45, v45, v99
	v_mul_f32_e32 v53, v42, v102
	v_cvt_pk_bf16_f32 v42, v48, v49
	v_cvt_pk_bf16_f32 v43, v44, v45
	v_cvt_pk_bf16_f32 v44, v53, v97
	v_mov_b32_e32 v97, 0
	v_mul_f32_e32 v46, v46, v103
	v_mul_f32_e32 v47, v47, v101
	v_cvt_pk_bf16_f32 v45, v46, v47
	global_store_dwordx4 v[32:33], v[42:45], off
	s_and_saveexec_b64 s[2:3], s[6:7]
	s_cbranch_execz .LBB0_1468
	v_lshl_add_u64 v[46:47], v[40:41], 0, v[56:57]
	v_add_co_u32_e32 v42, vcc, 0xffffc000, v46
	s_nop 1
	v_addc_co_u32_e32 v43, vcc, -1, v47, vcc
	v_mov_b64_e32 v[42:43], v[208:209]
	v_mov_b64_e32 v[44:45], v[210:211]
	v_add_co_u32_e32 v50, vcc, 0xffffd000, v46
	v_lshlrev_b32_e32 v100, 16, v44
	v_addc_co_u32_e32 v51, vcc, -1, v47, vcc
	global_load_dwordx4 v[46:49], v[76:77], off
	v_mov_b64_e32 v[92:93], v[212:213]
	v_mov_b64_e32 v[94:95], v[214:215]
	global_load_dwordx4 v[96:99], v[76:77], off offset:16
	v_lshlrev_b32_e32 v50, 16, v42
	v_and_b32_e32 v51, 0xffff0000, v42
	v_lshlrev_b32_e32 v42, 16, v43
	v_and_b32_e32 v43, 0xffff0000, v43
	v_and_b32_e32 v101, 0xffff0000, v44
	v_lshlrev_b32_e32 v44, 16, v45
	v_and_b32_e32 v45, 0xffff0000, v45
	s_waitcnt vmcnt(1)
	v_pk_mul_f32 v[46:47], v[46:47], v[50:51]
	s_waitcnt vmcnt(1)
	v_lshlrev_b32_e32 v50, 16, v92
	v_and_b32_e32 v51, 0xffff0000, v92
	v_pk_mul_f32 v[42:43], v[48:49], v[42:43]
	v_lshlrev_b32_e32 v48, 16, v93
	v_and_b32_e32 v49, 0xffff0000, v93
	s_waitcnt vmcnt(0)
	v_pk_mul_f32 v[96:97], v[96:97], v[100:101]
	v_lshlrev_b32_e32 v100, 16, v94
	v_and_b32_e32 v101, 0xffff0000, v94
	v_pk_mul_f32 v[44:45], v[98:99], v[44:45]
	v_lshlrev_b32_e32 v98, 16, v95
	v_and_b32_e32 v99, 0xffff0000, v95
	v_pk_fma_f32 v[50:51], v[46:47], v[50:51], 0 op_sel_hi:[1,1,0]
	v_pk_fma_f32 v[92:93], v[42:43], v[48:49], 0 op_sel_hi:[1,1,0]
	v_pk_fma_f32 v[94:95], v[96:97], v[100:101], 0 op_sel_hi:[1,1,0]
	v_pk_fma_f32 v[96:97], v[44:45], v[98:99], 0 op_sel_hi:[1,1,0]
.LBB0_1468:
	s_or_b64 exec, exec, s[2:3]
	v_lshl_add_u64 v[34:35], v[34:35], 0, v[56:57]
	v_mov_b64_e32 v[42:43], v[218:219]
	v_mov_b64_e32 v[44:45], v[220:221]
	v_lshl_add_u64 v[34:35], v[36:37], 0, v[56:57]
	v_mov_b64_e32 v[34:35], v[222:223]
	v_mov_b64_e32 v[36:37], v[224:225]
	s_nop 0
	global_load_dwordx4 v[46:49], v[78:79], off
	global_load_dwordx4 v[98:101], v[78:79], off offset:16
	s_waitcnt vmcnt(2)
	v_lshlrev_b32_e32 v104, 16, v34
	v_lshlrev_b32_e32 v102, 16, v42
	v_and_b32_e32 v103, 0xffff0000, v42
	v_lshlrev_b32_e32 v42, 16, v43
	v_and_b32_e32 v43, 0xffff0000, v43
	v_lshlrev_b32_e32 v106, 16, v44
	v_and_b32_e32 v107, 0xffff0000, v44
	v_lshlrev_b32_e32 v44, 16, v45
	v_and_b32_e32 v45, 0xffff0000, v45
	v_and_b32_e32 v105, 0xffff0000, v34
	v_lshlrev_b32_e32 v34, 16, v35
	v_and_b32_e32 v35, 0xffff0000, v35
	v_lshlrev_b32_e32 v108, 16, v36
	v_and_b32_e32 v109, 0xffff0000, v36
	v_lshlrev_b32_e32 v110, 16, v37
	v_and_b32_e32 v111, 0xffff0000, v37
	s_waitcnt vmcnt(1)
	v_pk_mul_f32 v[36:37], v[46:47], v[102:103]
	v_pk_mul_f32 v[42:43], v[48:49], v[42:43]
	s_waitcnt vmcnt(0)
	v_pk_mul_f32 v[46:47], v[98:99], v[106:107]
	v_pk_mul_f32 v[48:49], v[100:101], v[44:45]
	v_pk_fma_f32 v[44:45], v[36:37], v[104:105], v[50:51]
	v_pk_fma_f32 v[36:37], v[42:43], v[34:35], v[92:93]
	v_pk_fma_f32 v[34:35], v[46:47], v[108:109], v[94:95]
	v_pk_fma_f32 v[42:43], v[48:49], v[110:111], v[96:97]
	s_and_saveexec_b64 s[2:3], s[8:9]
	s_cbranch_execz .LBB0_1445
	v_lshl_add_u64 v[40:41], v[40:41], 0, v[56:57]
	v_add_co_u32_e32 v40, vcc, 0xa000, v40
	s_nop 1
	v_addc_co_u32_e32 v41, vcc, 0, v41, vcc
	v_mov_b64_e32 v[46:47], v[226:227]
	v_mov_b64_e32 v[48:49], v[228:229]
	v_mov_b64_e32 v[92:93], v[230:231]
	v_mov_b64_e32 v[94:95], v[232:233]
	global_load_dwordx4 v[96:99], v[80:81], off
	global_load_dwordx4 v[100:103], v[80:81], off offset:16
	s_waitcnt vmcnt(3)
	v_lshlrev_b32_e32 v40, 16, v46
	v_and_b32_e32 v41, 0xffff0000, v46
	v_lshlrev_b32_e32 v46, 16, v47
	v_and_b32_e32 v47, 0xffff0000, v47
	v_lshlrev_b32_e32 v104, 16, v48
	v_and_b32_e32 v105, 0xffff0000, v48
	v_lshlrev_b32_e32 v48, 16, v49
	v_and_b32_e32 v49, 0xffff0000, v49
	s_waitcnt vmcnt(2)
	v_lshlrev_b32_e32 v50, 16, v92
	v_and_b32_e32 v51, 0xffff0000, v92
	v_lshlrev_b32_e32 v92, 16, v93
	v_and_b32_e32 v93, 0xffff0000, v93
	v_lshlrev_b32_e32 v106, 16, v94
	v_and_b32_e32 v107, 0xffff0000, v94
	v_lshlrev_b32_e32 v94, 16, v95
	v_and_b32_e32 v95, 0xffff0000, v95
	s_waitcnt vmcnt(1)
	v_pk_mul_f32 v[40:41], v[96:97], v[40:41]
	v_pk_mul_f32 v[46:47], v[98:99], v[46:47]
	s_waitcnt vmcnt(0)
	v_pk_mul_f32 v[96:97], v[100:101], v[104:105]
	v_pk_mul_f32 v[48:49], v[102:103], v[48:49]
	v_pk_fma_f32 v[44:45], v[40:41], v[50:51], v[44:45]
	v_pk_fma_f32 v[36:37], v[46:47], v[92:93], v[36:37]
	v_pk_fma_f32 v[34:35], v[96:97], v[106:107], v[34:35]
	v_pk_fma_f32 v[42:43], v[48:49], v[94:95], v[42:43]
	s_branch .LBB0_1445
